# A1 specialised per wave class (tiles strictly above / below the diagonal block compute only M / only NAK,NRK,NRB; masks only on diagonal tiles; never-rewritten zero tiles stored once per chunk group);
# speedup vs baseline: 1.0056x; 1.0056x over previous
; #define LAS __attribute__((address_space(3)))
; __device__ __forceinline__ void rwkv_chunk_group(Frame& F, int bc, unsigned long long& tsub) {
;     ...
;         float offs = 0.f, tot = 0.f;
; #pragma unroll
;         for (int g = 0; g < 8; ++g) { const float x = *(const LAS float*)(L + L_GT + (g * 64 + ch) * 4); if (g < w) offs += x; tot += x; }
.LBB0_1418:
	v_cndmask_b32_e64 v182, v185, 0, s[82:83]
	v_readlane_b32 s66, v254, 40
	v_add_f32_e32 v47, v47, v182
	v_readlane_b32 s67, v254, 41

; #define GAS __attribute__((address_space(1)))
; #define LAS __attribute__((address_space(3)))
; __device__ __forceinline__ void rwkv_chunk_group(Frame& F, int bc, unsigned long long& tsub) {
;     ...
;         for (int tt = 0; tt < 8; ++tt) { const float kn = kkv[tt] * __builtin_amdgcn_rsqf(fmaxf(sq[tt], 1e-24f));
;             aa[tt] = -kn; bb[tt] = kn * icv[tt]; vbv[tt] = bq[tt] * vv[tt]; }
;         *(LAS float*)(L + L_GT + (w * 64 + ch) * 4) = run;
;         *(GAS v4u*)(VBp + ch * 64 + tb) = (v4u){pk2(vbv[0], vbv[1]), pk2(vbv[2], vbv[3]), pk2(vbv[4], vbv[5]), pk2(vbv[6], vbv[7])};
;         *(GAS v4u*)(Gp + ch * 64 + tb) = (v4u){pk2(ggv[0], ggv[1]), pk2(ggv[2], ggv[3]), pk2(ggv[4], ggv[5]), pk2(ggv[6], ggv[7])};
;         if (hh + 1 < RW_H) {
;             const bool has = (c * CH + tb > 0);
; #pragma unroll
;             for (int tt = 0; tt < 9; ++tt) { const size_t off = (size_t)(row0 + tb + tt - 1) * PRW + hnext * 64 + ch;
;                 if (tt > 0 || has) { raw[tt][0] = P[off]; raw[tt][1] = P[off + 512]; raw[tt][2] = P[off + 1024]; } }
;         }
;         LBAR();
;         float offs = 0.f, tot = 0.f;
; #pragma unroll
;         for (int g = 0; g < 8; ++g) { const float x = *(const LAS float*)(L + L_GT + (g * 64 + ch) * 4); if (g < w) offs += x; tot += x; }
;         const float etot = __expf(tot);
;         if (w == 0) *(LAS float*)(L + L_WC + ch * 4) = etot;
;         unsigned patt[4], pvt[4], pbh[4], pkh[4]; float hAt = 0.f, hBh = 0.f, hKh = 0.f;
;         float e_ex = __expf(offs);
; #pragma unroll
;         for (int tt = 0; tt < 8; ++tt) { const int t = tb + tt; const float cl = offs + ld[tt];
;             const float e_in = __expf(cl), e_inv = __builtin_amdgcn_rcpf(e_in), e_hat = etot * e_inv;
;             const float At = aa[tt] * e_ex, Bt = bb[tt] * e_inv, Kt = kp[tt] * e_inv, Rt = rr[tt] * e_in, Bh = bb[tt] * e_hat, Kh = kp[tt] * e_hat; e_ex = e_in;
;             *(LAS bf16*)(L + L_AT + t * LD + ch * 2) = (bf16)f2bf(At); *(LAS bf16*)(L + L_BT + t * LD + ch * 2) = (bf16)f2bf(Bt);
;             *(LAS bf16*)(L + L_KT + t * LD + ch * 2) = (bf16)f2bf(Kt); *(LAS bf16*)(L + L_RT + t * LD + ch * 2) = (bf16)f2bf(Rt);
;             if (tt & 1) { patt[tt >> 1] = pk2(hAt, At); pvt[tt >> 1] = pk2(vv[tt - 1], vv[tt]); pbh[tt >> 1] = pk2(hBh, Bh); pkh[tt >> 1] = pk2(hKh, Kh); }
;             hAt = At; hBh = Bh; hKh = Kh;
;         }
	s_mov_b32 s17, s16
	v_cndmask_b32_e64 v47, v182, v47, s[66:67]
	v_readlane_b32 s66, v254, 42
	v_add_f32_e32 v102, v102, v47
	v_readlane_b32 s67, v254, 43
	s_nop 1
	v_cndmask_b32_e64 v47, v47, v102, s[66:67]
	v_readlane_b32 s66, v254, 44
	v_add_f32_e32 v102, v103, v47
	v_readlane_b32 s67, v254, 45
	s_nop 1
	v_cndmask_b32_e64 v47, v47, v102, s[66:67]
	v_readlane_b32 s66, v254, 46
	v_add_f32_e32 v98, v98, v47
	v_readlane_b32 s67, v254, 47
	s_nop 1
	v_cndmask_b32_e64 v47, v47, v98, s[66:67]
	v_readlane_b32 s66, v254, 48
	v_add_f32_e32 v98, v99, v47
	v_readlane_b32 s67, v254, 49
	v_max_f32_e64 v99, s77, s77
	v_max_f32_e32 v99, 0x179abe15, v99
	v_cndmask_b32_e64 v47, v47, v98, s[66:67]
	v_readlane_b32 s66, v254, 50
	v_max_f32_e64 v98, s71, s71
	v_add_f32_e32 v96, v96, v47
	v_readlane_b32 s67, v254, 51
	v_max_f32_e32 v98, 0x179abe15, v98
	v_rsq_f32_e32 v98, v98
	v_cndmask_b32_e64 v47, v47, v96, s[66:67]
	v_rsq_f32_e32 v99, v99
	v_add_f32_e32 v102, v97, v47
	v_max_f32_e64 v97, s14, s14
	v_readlane_b32 s14, v254, 53
	v_readlane_b32 s15, v254, 54
	v_pk_mul_f32 v[88:89], v[88:89], v[98:99]
	v_max_f32_e64 v98, s69, s69
	v_cndmask_b32_e64 v47, v47, v102, s[14:15]
	v_max_f32_e64 v99, s70, s70
	v_add_f32_e32 v102, v177, v47
	v_max_f32_e32 v98, 0x179abe15, v98
	v_max_f32_e32 v99, 0x179abe15, v99
	v_mul_f32_e32 v102, 0x3fb8aa3b, v102
	v_max_f32_e64 v96, s93, s93
	v_rsq_f32_e32 v98, v98
	v_rsq_f32_e32 v99, v99
	v_exp_f32_e32 v103, v102
	v_max_f32_e32 v96, 0x179abe15, v96
	v_max_f32_e32 v97, 0x179abe15, v97
	v_rsq_f32_e32 v96, v96
	v_rsq_f32_e32 v97, v97
	v_pk_mul_f32 v[98:99], v[80:81], v[98:99]
	v_rcp_f32_e32 v80, v103
	v_mul_f32_e32 v81, 0x3fb8aa3b, v47
	v_pk_mul_f32 v[96:97], v[100:101], v[96:97]
	v_exp_f32_e32 v102, v81
	v_pk_mul_f32 v[38:39], v[38:39], v[96:97]
	s_mul_i32 s14, s16, 0x480
	v_mul_f32_e32 v81, v38, v80
	v_pk_mul_f32 v[186:187], v[86:87], v[98:99]
	v_mul_f32_e32 v86, v40, v80
	v_mul_f32_e32 v87, v173, v103
	v_cvt_pk_bf16_f32 v81, v81, s0
	v_add_u32_e32 v173, s14, v58
	ds_write_b16 v173, v81 offset:9216
	v_cvt_pk_bf16_f32 v81, v86, s0
	v_add_f32_e32 v86, v176, v47
	v_mul_f32_e32 v86, 0x3fb8aa3b, v86
	v_max_f32_e64 v100, s64, s64
	v_max_f32_e64 v101, s65, s65
	v_exp_f32_e32 v176, v86
	v_max_f32_e32 v100, 0x179abe15, v100
	v_max_f32_e32 v101, 0x179abe15, v101
	v_rsq_f32_e32 v100, v100
	v_rsq_f32_e32 v101, v101
	ds_write_b16 v173, v81 offset:18432
	v_cvt_pk_bf16_f32 v81, v87, s0
	ds_write_b16 v173, v81 offset:27648
	v_rcp_f32_e32 v81, v176
	v_pk_mul_f32 v[44:45], v[44:45], v[100:101]
	v_pk_mul_f32 v[86:87], v[102:103], v[96:97] neg_lo:[0,1] neg_hi:[0,1]
	v_pk_mul_f32 v[100:101], v[94:95], v[44:45]
	v_cvt_pk_bf16_f32 v94, v86, s0
	ds_write_b16 v173, v94
	v_mul_f32_e32 v94, v39, v81
	v_mul_f32_e32 v95, v41, v81
	v_cvt_pk_bf16_f32 v94, v94, s0
	v_mul_f32_e32 v96, v174, v176
	ds_write_b16 v173, v94 offset:9360
	v_cvt_pk_bf16_f32 v94, v95, s0
	ds_write_b16 v173, v94 offset:18576
	v_cvt_pk_bf16_f32 v94, v96, s0
	ds_write_b16 v173, v94 offset:27792
	v_add_f32_e32 v94, v179, v47
	v_mul_f32_e32 v94, 0x3fb8aa3b, v94
	v_exp_f32_e32 v177, v94
	v_pk_mul_f32 v[82:83], v[82:83], v[88:89]
	v_pk_mul_f32 v[80:81], v[46:47], v[80:81] op_sel_hi:[0,1]
	v_pk_mul_f32 v[40:41], v[40:41], v[80:81]
	v_rcp_f32_e32 v96, v177
	v_pk_mul_f32 v[94:95], v[38:39], v[80:81]
	v_cvt_pk_bf16_f32 v80, v36, v37
	v_cvt_pk_bf16_f32 v97, v87, s0
	v_mul_f32_e32 v36, v82, v96
	v_cvt_pk_bf16_f32 v36, v36, s0
	ds_write_b16 v173, v36 offset:9504
	v_add_f32_e32 v36, v181, v47
	v_mul_f32_e32 v36, 0x3fb8aa3b, v36
	v_exp_f32_e32 v36, v36
	ds_write_b16 v173, v97 offset:144
	v_mul_f32_e32 v37, v78, v96
	v_mul_f32_e32 v39, v175, v177
	v_rcp_f32_e32 v97, v36
	v_cvt_pk_bf16_f32 v37, v37, s0
	v_cvt_pk_bf16_f32 v38, v86, v87
	v_cvt_pk_bf16_f32 v86, v94, v95
	v_cvt_pk_bf16_f32 v94, v40, v41
	ds_write_b16 v173, v37 offset:18720
	v_cvt_pk_bf16_f32 v37, v39, s0
	v_pk_mul_f32 v[40:41], v[176:177], v[88:89] neg_lo:[0,1] neg_hi:[0,1]
	ds_write_b16 v173, v37 offset:27936
	v_cvt_pk_bf16_f32 v37, v40, s0
	ds_write_b16 v173, v37 offset:288
	v_mul_f32_e32 v37, v83, v97
	v_mul_f32_e32 v39, v79, v97
	v_cvt_pk_bf16_f32 v37, v37, s0
	v_mul_f32_e32 v81, v178, v36
	ds_write_b16 v173, v37 offset:9648
	v_cvt_pk_bf16_f32 v37, v39, s0
	ds_write_b16 v173, v37 offset:18864
	v_cvt_pk_bf16_f32 v37, v81, s0
	ds_write_b16 v173, v37 offset:28080
	v_add_f32_e32 v37, v184, v47
	v_mul_f32_e32 v37, 0x3fb8aa3b, v37
	v_exp_f32_e32 v37, v37
	v_cvt_pk_bf16_f32 v39, v40, v41
	v_cvt_pk_bf16_f32 v87, v41, s0
	v_cvt_pk_bf16_f32 v81, v76, v77
	v_rcp_f32_e32 v40, v37
	v_mul_f32_e32 v77, v180, v37
	v_pk_mul_f32 v[36:37], v[36:37], v[98:99] neg_lo:[0,1] neg_hi:[0,1]
	v_pk_mul_f32 v[88:89], v[46:47], v[96:97] op_sel_hi:[0,1]
	v_mul_f32_e32 v41, v186, v40
	v_mul_f32_e32 v76, v90, v40
	v_cvt_pk_bf16_f32 v41, v41, s0
	ds_write_b16 v173, v41 offset:9792
	v_cvt_pk_bf16_f32 v41, v76, s0
	v_add_f32_e32 v76, v190, v47
	v_mul_f32_e32 v76, 0x3fb8aa3b, v76
	v_exp_f32_e32 v76, v76
	ds_write_b16 v173, v41 offset:19008
	v_cvt_pk_bf16_f32 v41, v77, s0
	ds_write_b16 v173, v41 offset:28224
	v_rcp_f32_e32 v41, v76
	v_cvt_pk_bf16_f32 v77, v36, s0
	v_pk_mul_f32 v[78:79], v[78:79], v[88:89]
	ds_write_b16 v173, v77 offset:576
	v_mul_f32_e32 v77, v187, v41
	v_cvt_pk_bf16_f32 v95, v78, v79
	v_mul_f32_e32 v78, v91, v41
	v_cvt_pk_bf16_f32 v77, v77, s0
	v_mul_f32_e32 v79, v183, v76
	ds_write_b16 v173, v77 offset:9936
	v_cvt_pk_bf16_f32 v77, v78, s0
	ds_write_b16 v173, v77 offset:19152
	v_cvt_pk_bf16_f32 v77, v79, s0
	ds_write_b16 v173, v77 offset:28368
	v_add_f32_e32 v77, v192, v47
	v_mul_f32_e32 v77, 0x3fb8aa3b, v77
	v_exp_f32_e32 v77, v77
; #define LAS __attribute__((address_space(3)))
; __device__ __forceinline__ void rwkv_chunk_group(Frame& F, int bc, unsigned long long& tsub) {
;     ...
;         for (int tt = 0; tt < 8; ++tt) { const int t = tb + tt; const float cl = offs + ld[tt];
;             const float e_in = __expf(cl), e_inv = __builtin_amdgcn_rcpf(e_in), e_hat = etot * e_inv;
;             const float At = aa[tt] * e_ex, Bt = bb[tt] * e_inv, Kt = kp[tt] * e_inv, Rt = rr[tt] * e_in, Bh = bb[tt] * e_hat, Kh = kp[tt] * e_hat; e_ex = e_in;
;             *(LAS bf16*)(L + L_AT + t * LD + ch * 2) = (bf16)f2bf(At); *(LAS bf16*)(L + L_BT + t * LD + ch * 2) = (bf16)f2bf(Bt);
;             *(LAS bf16*)(L + L_KT + t * LD + ch * 2) = (bf16)f2bf(Kt); *(LAS bf16*)(L + L_RT + t * LD + ch * 2) = (bf16)f2bf(Rt);
;             if (tt & 1) { patt[tt >> 1] = pk2(hAt, At); pvt[tt >> 1] = pk2(vv[tt - 1], vv[tt]); pbh[tt >> 1] = pk2(hBh, Bh); pkh[tt >> 1] = pk2(hKh, Kh); }
;             hAt = At; hBh = Bh; hKh = Kh;
;         }
;         *(LAS v4u*)(L + L_ATT + ch * LD + tb * 2) = (v4u){patt[0], patt[1], patt[2], patt[3]};
;         *(LAS v4u*)(L + L_VT + ch * LD + tb * 2) = (v4u){pvt[0], pvt[1], pvt[2], pvt[3]};
;         *(LAS v4u*)(L + L_BH + ch * LD + tb * 2) = (v4u){pbh[0], pbh[1], pbh[2], pbh[3]};
;         *(LAS v4u*)(L + L_KH + ch * LD + tb * 2) = (v4u){pkh[0], pkh[1], pkh[2], pkh[3]};
;         LBAR();
;     ...
;     for (int q = 0; q < 2; ++q) { const int tw = 2 * w + q, p0 = 16 * (tw >> 2), q0 = 16 * (tw & 3);
;         f32x4 m = mm_tile(L + L_AT, LD, q0, L + L_BT, LD, p0, 2, Z4, fr, fq);
;         f32x4 nak = mm_tile(L + L_KT, LD, q0, L + L_AT, LD, p0, 2, Z4, fr, fq);
;         f32x4 nrk = mm_tile(L + L_KT, LD, q0, L + L_RT, LD, p0, 2, Z4, fr, fq);
;         f32x4 nrb = mm_tile(L + L_BT, LD, q0, L + L_RT, LD, p0, 2, Z4, fr, fq);
;         f32x4 tt;
;         const int p = p0 + fr;
; #pragma unroll
;         for (int v = 0; v < 4; ++v) { const int qq = q0 + 4 * fq + v;
;             if (!(p < qq)) m[v] = 0.f;
;             if (!(qq < p)) nak[v] = 0.f;
;             if (!(qq <= p)) { nrk[v] = 0.f; nrb[v] = 0.f; }
;             tt[v] = (p == qq) ? 1.f : 0.f; }
;         const int o = p * LD + (q0 + 4 * fq) * 2;
;         st4_lds(L + L_M + o, m); st4t_lds(L + L_MT, p, q0 + 4 * fq, m); st4_lds(L + L_NAK + o, nak); st4_lds(L + L_NRK + o, nrk); st4_lds(L + L_NRB + o, nrb); st4_lds(L + L_TT + o, tt);
;     }
	v_pk_mul_f32 v[40:41], v[46:47], v[40:41] op_sel_hi:[0,1]
	v_pk_mul_f32 v[82:83], v[82:83], v[88:89]
	v_pk_mul_f32 v[78:79], v[90:91], v[40:41]
	v_pk_mul_f32 v[88:89], v[186:187], v[40:41]
	v_cvt_pk_bf16_f32 v40, v36, v37
	v_rcp_f32_e32 v36, v77
	ds_write_b16 v173, v87 offset:432
	v_cvt_pk_bf16_f32 v87, v82, v83
	v_cvt_pk_bf16_f32 v82, v37, s0
	v_mul_f32_e32 v37, v100, v36
	v_mul_f32_e32 v41, v42, v36
	v_cvt_pk_bf16_f32 v37, v37, s0
	ds_write_b16 v173, v37 offset:10080
	v_cvt_pk_bf16_f32 v37, v41, s0
	v_add_f32_e32 v41, v52, v47
	v_mul_f32_e32 v41, 0x3fb8aa3b, v41
	v_exp_f32_e32 v41, v41
	v_cvt_pk_bf16_f32 v96, v78, v79
	v_mul_f32_e32 v78, v188, v77
	ds_write_b16 v173, v37 offset:19296
	v_cvt_pk_bf16_f32 v37, v78, s0
	ds_write_b16 v173, v37 offset:28512
	v_rcp_f32_e32 v37, v41
	v_pk_mul_f32 v[44:45], v[76:77], v[44:45] neg_lo:[0,1] neg_hi:[0,1]
	v_mul_f32_e32 v41, v191, v41
	v_cvt_pk_bf16_f32 v47, v44, s0
	ds_write_b16 v173, v47 offset:864
	v_mul_f32_e32 v47, v101, v37
	v_mul_f32_e32 v52, v43, v37
	v_cvt_pk_bf16_f32 v47, v47, s0
	ds_write_b16 v173, v47 offset:10224
	v_cvt_pk_bf16_f32 v47, v52, s0
	v_cvt_pk_bf16_f32 v41, v41, s0
	v_pk_mul_f32 v[36:37], v[46:47], v[36:37] op_sel_hi:[0,1]
	v_cvt_pk_bf16_f32 v76, v45, s0
	ds_write_b16 v173, v41 offset:28656
	v_pk_mul_f32 v[42:43], v[42:43], v[36:37]
	v_pk_mul_f32 v[36:37], v[100:101], v[36:37]
	v_cvt_pk_bf16_f32 v41, v44, v45
	ds_write_b16 v173, v82 offset:720
	v_cvt_pk_bf16_f32 v82, v84, v85
	v_cvt_pk_bf16_f32 v88, v88, v89
	ds_write_b16 v173, v76 offset:1008
	ds_write_b16 v173, v47 offset:19440
	v_cvt_pk_bf16_f32 v97, v42, v43
	v_cvt_pk_bf16_f32 v89, v36, v37
	v_cvt_pk_bf16_f32 v83, v92, v93
	ds_write_b128 v141, v[38:41] offset:36864
	ds_write_b128 v141, v[80:83] offset:46080
	ds_write_b128 v141, v[86:89] offset:55296
	ds_write_b128 v141, v[94:97] offset:64512
	s_waitcnt lgkmcnt(0)
	s_barrier
	v_add_u32_e32 v76, v106, v110
	v_add_u32_e32 v77, v106, v128
	v_add_u32_e32 v97, 0x12000, v127
	v_add_u32_e32 v98, 0x12000, v129
	v_mov_b32_e32 v174, 0
	v_mov_b32_e32 v175, 0
	s_and_b64 vcc, exec, s[78:79]
	s_cbranch_vccz .La1_UU
	s_and_b64 vcc, exec, s[84:85]
	s_cbranch_vccz .La1_Lx
	ds_read_b128 v[176:179], v76 offset:0
	ds_read_b128 v[180:183], v107 offset:9216
	ds_read_b128 v[184:187], v76 offset:18432
	ds_read_b128 v[188:191], v107 offset:0
	ds_read_b128 v[192:195], v107 offset:27648
	ds_read_b128 v[196:199], v76 offset:9216
	ds_read_b128 v[224:227], v77 offset:0
	ds_read_b128 v[228:231], v76 offset:64
	ds_read_b128 v[232:235], v107 offset:9280
	ds_read_b128 v[236:239], v76 offset:18496
	ds_read_b128 v[240:243], v107 offset:64
	ds_read_b128 v[244:247], v107 offset:27712
	ds_read_b128 v[248:251], v76 offset:9280
	ds_read_b128 v[148:151], v77 offset:64
	s_waitcnt lgkmcnt(12)
	v_mfma_f32_16x16x32_bf16 v[78:81], v[176:179], v[180:183], 0
	s_waitcnt lgkmcnt(10)
	v_mfma_f32_16x16x32_bf16 v[82:85], v[184:187], v[188:191], 0
	s_waitcnt lgkmcnt(9)
	v_mfma_f32_16x16x32_bf16 v[86:89], v[184:187], v[192:195], 0
	s_waitcnt lgkmcnt(8)
	v_mfma_f32_16x16x32_bf16 v[90:93], v[196:199], v[192:195], 0
	s_waitcnt lgkmcnt(7)
	v_mfma_f32_16x16x32_bf16 v[36:39], v[224:227], v[180:183], 0
	s_waitcnt lgkmcnt(5)
	v_mfma_f32_16x16x32_bf16 v[78:81], v[228:231], v[232:235], v[78:81]
	s_waitcnt lgkmcnt(3)
	v_mfma_f32_16x16x32_bf16 v[82:85], v[236:239], v[240:243], v[82:85]
	s_waitcnt lgkmcnt(2)
	v_mfma_f32_16x16x32_bf16 v[86:89], v[236:239], v[244:247], v[86:89]
	s_waitcnt lgkmcnt(1)
	v_mfma_f32_16x16x32_bf16 v[90:93], v[248:251], v[244:247], v[90:93]
	s_waitcnt lgkmcnt(0)
	v_mfma_f32_16x16x32_bf16 v[36:39], v[148:151], v[232:235], v[36:39]
	s_nop 7
	s_nop 1
	v_cndmask_b32_e64 v78, 0, v78, s[48:49]
	v_cndmask_b32_e64 v79, v79, 0, s[50:51]
	v_cndmask_b32_e64 v80, 0, v80, s[52:53]
	v_cndmask_b32_e64 v81, 0, v81, s[54:55]
	v_cndmask_b32_e64 v82, 0, v82, s[50:51]
	v_cndmask_b32_e64 v83, 0, v83, s[40:41]
	v_cndmask_b32_e64 v84, 0, v84, s[38:39]
	v_cndmask_b32_e64 v85, 0, v85, s[36:37]
	v_cndmask_b32_e64 v86, v86, 0, s[48:49]
	v_cndmask_b32_e64 v87, 0, v87, s[50:51]
	v_cndmask_b32_e64 v88, v88, 0, s[52:53]
	v_cndmask_b32_e64 v89, v89, 0, s[54:55]
	v_cndmask_b32_e64 v90, v90, 0, s[48:49]
	v_cndmask_b32_e64 v91, 0, v91, s[50:51]
	v_cndmask_b32_e64 v92, v92, 0, s[52:53]
	v_cndmask_b32_e64 v93, v93, 0, s[54:55]
	v_cvt_pk_bf16_f32 v78, v78, v79
	v_cvt_pk_bf16_f32 v79, v80, v81
	v_cvt_pk_bf16_f32 v82, v82, v83
	v_cvt_pk_bf16_f32 v83, v84, v85
	v_cvt_pk_bf16_f32 v86, v86, v87
	v_cvt_pk_bf16_f32 v87, v88, v89
	v_cvt_pk_bf16_f32 v90, v90, v91
	v_cvt_pk_bf16_f32 v91, v92, v93
	ds_write_b64 v97, v[78:79]
	ds_write_b64 v97, v[82:83] offset:27648
	ds_write_b64 v97, v[86:87] offset:36864
	ds_write_b64 v97, v[90:91] offset:46080
	ds_write_b64 v97, v[60:61] offset:18432
	v_cvt_pk_bf16_f32 v36, v36, v37
	v_cvt_pk_bf16_f32 v37, v38, v39
	ds_write_b64 v98, v[36:37]
	s_cmp_lg_u32 s12, 1
	s_cbranch_scc1 .La1_DU_b_nz
	ds_write_b64 v98, v[174:175] offset:27648
	ds_write_b64 v98, v[174:175] offset:36864
	ds_write_b64 v98, v[174:175] offset:46080
	ds_write_b64 v98, v[174:175] offset:18432
.La1_DU_b_nz:
	s_waitcnt lgkmcnt(0)
	s_barrier
	s_branch .La1_done
; __device__ __forceinline__ void st4_lds(LAS unsigned char* p, f32x4 v) { v2u w; w.x = pk2(v[0], v[1]); w.y = pk2(v[2], v[3]); *(LAS v2u*)p = w; }
; __device__ __forceinline__ void rwkv_chunk_group(Frame& F, int bc, unsigned long long& tsub) {
;     ...
;     for (int q = 0; q < 2; ++q) { const int tw = 2 * w + q, p0 = 16 * (tw >> 2), q0 = 16 * (tw & 3);
;         f32x4 m = mm_tile(L + L_AT, LD, q0, L + L_BT, LD, p0, 2, Z4, fr, fq);
;         f32x4 nak = mm_tile(L + L_KT, LD, q0, L + L_AT, LD, p0, 2, Z4, fr, fq);
;         f32x4 nrk = mm_tile(L + L_KT, LD, q0, L + L_RT, LD, p0, 2, Z4, fr, fq);
;         f32x4 nrb = mm_tile(L + L_BT, LD, q0, L + L_RT, LD, p0, 2, Z4, fr, fq);
;         f32x4 tt;
;         const int p = p0 + fr;
; #pragma unroll
;         for (int v = 0; v < 4; ++v) { const int qq = q0 + 4 * fq + v;
;             if (!(p < qq)) m[v] = 0.f;
;             if (!(qq < p)) nak[v] = 0.f;
;             if (!(qq <= p)) { nrk[v] = 0.f; nrb[v] = 0.f; }
;             tt[v] = (p == qq) ? 1.f : 0.f; }
;         const int o = p * LD + (q0 + 4 * fq) * 2;
;         st4_lds(L + L_M + o, m); st4t_lds(L + L_MT, p, q0 + 4 * fq, m); st4_lds(L + L_NAK + o, nak); st4_lds(L + L_NRK + o, nrk); st4_lds(L + L_NRB + o, nrb); st4_lds(L + L_TT + o, tt);
;     }
.La1_Lx:
	s_and_b64 vcc, exec, s[90:91]
	s_cbranch_vccz .La1_LL
	ds_read_b128 v[176:179], v76 offset:18432
	ds_read_b128 v[180:183], v107 offset:0
	ds_read_b128 v[184:187], v107 offset:27648
	ds_read_b128 v[188:191], v76 offset:9216
	ds_read_b128 v[192:195], v77 offset:0
	ds_read_b128 v[196:199], v107 offset:9216
	ds_read_b128 v[224:227], v77 offset:18432
	ds_read_b128 v[228:231], v77 offset:9216
	ds_read_b128 v[232:235], v76 offset:18496
	ds_read_b128 v[236:239], v107 offset:64
	ds_read_b128 v[240:243], v107 offset:27712
	ds_read_b128 v[244:247], v76 offset:9280
	ds_read_b128 v[248:251], v77 offset:64
	ds_read_b128 v[148:151], v107 offset:9280
	ds_read_b128 v[164:167], v77 offset:18496
	s_waitcnt lgkmcnt(13)
	v_mfma_f32_16x16x32_bf16 v[82:85], v[176:179], v[180:183], 0
	ds_read_b128 v[168:171], v77 offset:9280
	s_waitcnt lgkmcnt(13)
	v_mfma_f32_16x16x32_bf16 v[86:89], v[176:179], v[184:187], 0
	s_waitcnt lgkmcnt(12)
	v_mfma_f32_16x16x32_bf16 v[90:93], v[188:191], v[184:187], 0
	s_waitcnt lgkmcnt(10)
	v_mfma_f32_16x16x32_bf16 v[36:39], v[192:195], v[196:199], 0
	s_waitcnt lgkmcnt(9)
	v_mfma_f32_16x16x32_bf16 v[40:43], v[224:227], v[180:183], 0
	v_mfma_f32_16x16x32_bf16 v[44:47], v[224:227], v[184:187], 0
	s_waitcnt lgkmcnt(8)
	v_mfma_f32_16x16x32_bf16 v[100:103], v[228:231], v[184:187], 0
	s_waitcnt lgkmcnt(6)
	v_mfma_f32_16x16x32_bf16 v[82:85], v[232:235], v[236:239], v[82:85]
	s_waitcnt lgkmcnt(5)
	v_mfma_f32_16x16x32_bf16 v[86:89], v[232:235], v[240:243], v[86:89]
	s_waitcnt lgkmcnt(4)
	v_mfma_f32_16x16x32_bf16 v[90:93], v[244:247], v[240:243], v[90:93]
	s_waitcnt lgkmcnt(2)
	v_mfma_f32_16x16x32_bf16 v[36:39], v[248:251], v[148:151], v[36:39]
	s_waitcnt lgkmcnt(1)
	v_mfma_f32_16x16x32_bf16 v[40:43], v[164:167], v[236:239], v[40:43]
	v_mfma_f32_16x16x32_bf16 v[44:47], v[164:167], v[240:243], v[44:47]
	s_waitcnt lgkmcnt(0)
	v_mfma_f32_16x16x32_bf16 v[100:103], v[168:171], v[240:243], v[100:103]
	s_nop 7
	s_nop 1
	v_cvt_pk_bf16_f32 v82, v82, v83
	v_cvt_pk_bf16_f32 v83, v84, v85
	v_cvt_pk_bf16_f32 v86, v86, v87
	v_cvt_pk_bf16_f32 v87, v88, v89
	v_cvt_pk_bf16_f32 v90, v90, v91
	v_cvt_pk_bf16_f32 v91, v92, v93
	ds_write_b64 v97, v[82:83] offset:27648
	ds_write_b64 v97, v[86:87] offset:36864
	ds_write_b64 v97, v[90:91] offset:46080
	ds_write_b64 v97, v[174:175]
	ds_write_b64 v97, v[174:175] offset:18432
	v_cndmask_b32_e64 v36, 0, v36, s[56:57]
	v_cndmask_b32_e64 v37, v37, 0, s[58:59]
	v_cndmask_b32_e64 v38, 0, v38, s[60:61]
	v_cndmask_b32_e64 v39, 0, v39, s[62:63]
	v_cndmask_b32_e64 v40, 0, v40, s[58:59]
	v_cndmask_b32_e64 v41, 0, v41, s[46:47]
	v_cndmask_b32_e64 v42, 0, v42, s[44:45]
	v_cndmask_b32_e64 v43, 0, v43, s[42:43]
	v_cndmask_b32_e64 v44, v44, 0, s[56:57]
	v_cndmask_b32_e64 v45, 0, v45, s[58:59]
	v_cndmask_b32_e64 v46, v46, 0, s[60:61]
	v_cndmask_b32_e64 v47, v47, 0, s[62:63]
	v_cndmask_b32_e64 v100, v100, 0, s[56:57]
	v_cndmask_b32_e64 v101, 0, v101, s[58:59]
	v_cndmask_b32_e64 v102, v102, 0, s[60:61]
	v_cndmask_b32_e64 v103, v103, 0, s[62:63]
	v_cvt_pk_bf16_f32 v36, v36, v37
	v_cvt_pk_bf16_f32 v37, v38, v39
	v_cvt_pk_bf16_f32 v40, v40, v41
	v_cvt_pk_bf16_f32 v41, v42, v43
	v_cvt_pk_bf16_f32 v44, v44, v45
	v_cvt_pk_bf16_f32 v45, v46, v47
	v_cvt_pk_bf16_f32 v100, v100, v101
	v_cvt_pk_bf16_f32 v101, v102, v103
	ds_write_b64 v98, v[36:37]
	ds_write_b64 v98, v[40:41] offset:27648
	ds_write_b64 v98, v[44:45] offset:36864
	ds_write_b64 v98, v[100:101] offset:46080
	ds_write_b64 v98, v[72:73] offset:18432
	s_waitcnt lgkmcnt(0)
	s_barrier
	s_branch .La1_done
; __device__ __forceinline__ void st4_lds(LAS unsigned char* p, f32x4 v) { v2u w; w.x = pk2(v[0], v[1]); w.y = pk2(v[2], v[3]); *(LAS v2u*)p = w; }
; __device__ __forceinline__ void rwkv_chunk_group(Frame& F, int bc, unsigned long long& tsub) {
;     ...
;     for (int q = 0; q < 2; ++q) { const int tw = 2 * w + q, p0 = 16 * (tw >> 2), q0 = 16 * (tw & 3);
;         f32x4 m = mm_tile(L + L_AT, LD, q0, L + L_BT, LD, p0, 2, Z4, fr, fq);
;         f32x4 nak = mm_tile(L + L_KT, LD, q0, L + L_AT, LD, p0, 2, Z4, fr, fq);
;         f32x4 nrk = mm_tile(L + L_KT, LD, q0, L + L_RT, LD, p0, 2, Z4, fr, fq);
;         f32x4 nrb = mm_tile(L + L_BT, LD, q0, L + L_RT, LD, p0, 2, Z4, fr, fq);
;         f32x4 tt;
;         const int p = p0 + fr;
; #pragma unroll
;         for (int v = 0; v < 4; ++v) { const int qq = q0 + 4 * fq + v;
;             if (!(p < qq)) m[v] = 0.f;
;             if (!(qq < p)) nak[v] = 0.f;
;             if (!(qq <= p)) { nrk[v] = 0.f; nrb[v] = 0.f; }
;             tt[v] = (p == qq) ? 1.f : 0.f; }
;         const int o = p * LD + (q0 + 4 * fq) * 2;
;         st4_lds(L + L_M + o, m); st4t_lds(L + L_MT, p, q0 + 4 * fq, m); st4_lds(L + L_NAK + o, nak); st4_lds(L + L_NRK + o, nrk); st4_lds(L + L_NRB + o, nrb); st4_lds(L + L_TT + o, tt);
;     }
.La1_LL:
	ds_read_b128 v[176:179], v76 offset:18432
	ds_read_b128 v[180:183], v107 offset:0
	ds_read_b128 v[184:187], v107 offset:27648
	ds_read_b128 v[188:191], v76 offset:9216
	ds_read_b128 v[192:195], v77 offset:18432
	ds_read_b128 v[196:199], v77 offset:9216
	ds_read_b128 v[224:227], v76 offset:18496
	ds_read_b128 v[228:231], v107 offset:64
	ds_read_b128 v[232:235], v107 offset:27712
	ds_read_b128 v[236:239], v76 offset:9280
	ds_read_b128 v[240:243], v77 offset:18496
	ds_read_b128 v[244:247], v77 offset:9280
	s_waitcnt lgkmcnt(10)
	v_mfma_f32_16x16x32_bf16 v[82:85], v[176:179], v[180:183], 0
	s_waitcnt lgkmcnt(9)
	v_mfma_f32_16x16x32_bf16 v[86:89], v[176:179], v[184:187], 0
	s_waitcnt lgkmcnt(8)
	v_mfma_f32_16x16x32_bf16 v[90:93], v[188:191], v[184:187], 0
	s_waitcnt lgkmcnt(7)
	v_mfma_f32_16x16x32_bf16 v[40:43], v[192:195], v[180:183], 0
	v_mfma_f32_16x16x32_bf16 v[44:47], v[192:195], v[184:187], 0
	s_waitcnt lgkmcnt(6)
	v_mfma_f32_16x16x32_bf16 v[100:103], v[196:199], v[184:187], 0
	s_waitcnt lgkmcnt(4)
	v_mfma_f32_16x16x32_bf16 v[82:85], v[224:227], v[228:231], v[82:85]
	s_waitcnt lgkmcnt(3)
	v_mfma_f32_16x16x32_bf16 v[86:89], v[224:227], v[232:235], v[86:89]
	s_waitcnt lgkmcnt(2)
	v_mfma_f32_16x16x32_bf16 v[90:93], v[236:239], v[232:235], v[90:93]
	s_waitcnt lgkmcnt(1)
	v_mfma_f32_16x16x32_bf16 v[40:43], v[240:243], v[228:231], v[40:43]
	v_mfma_f32_16x16x32_bf16 v[44:47], v[240:243], v[232:235], v[44:47]
	s_waitcnt lgkmcnt(0)
	v_mfma_f32_16x16x32_bf16 v[100:103], v[244:247], v[232:235], v[100:103]
	s_nop 7
	s_nop 1
	v_cvt_pk_bf16_f32 v82, v82, v83
	v_cvt_pk_bf16_f32 v83, v84, v85
	v_cvt_pk_bf16_f32 v86, v86, v87
	v_cvt_pk_bf16_f32 v87, v88, v89
	v_cvt_pk_bf16_f32 v90, v90, v91
	v_cvt_pk_bf16_f32 v91, v92, v93
	ds_write_b64 v97, v[82:83] offset:27648
	ds_write_b64 v97, v[86:87] offset:36864
	ds_write_b64 v97, v[90:91] offset:46080
	ds_write_b64 v97, v[174:175]
	ds_write_b64 v97, v[174:175] offset:18432
	v_cvt_pk_bf16_f32 v40, v40, v41
	v_cvt_pk_bf16_f32 v41, v42, v43
	v_cvt_pk_bf16_f32 v44, v44, v45
	v_cvt_pk_bf16_f32 v45, v46, v47
	v_cvt_pk_bf16_f32 v100, v100, v101
	v_cvt_pk_bf16_f32 v101, v102, v103
	ds_write_b64 v98, v[40:41] offset:27648
	ds_write_b64 v98, v[44:45] offset:36864
	ds_write_b64 v98, v[100:101] offset:46080
	ds_write_b64 v98, v[174:175]
	ds_write_b64 v98, v[174:175] offset:18432
	s_waitcnt lgkmcnt(0)
	s_barrier
	s_branch .La1_done
.La1_UU:
	ds_read_b128 v[176:179], v76 offset:0
	ds_read_b128 v[180:183], v107 offset:9216
	ds_read_b128 v[184:187], v77 offset:0
	ds_read_b128 v[188:191], v76 offset:64
	ds_read_b128 v[192:195], v107 offset:9280
	ds_read_b128 v[196:199], v77 offset:64
	s_waitcnt lgkmcnt(4)
	v_mfma_f32_16x16x32_bf16 v[78:81], v[176:179], v[180:183], 0
	s_waitcnt lgkmcnt(3)
	v_mfma_f32_16x16x32_bf16 v[36:39], v[184:187], v[180:183], 0
	s_waitcnt lgkmcnt(1)
	v_mfma_f32_16x16x32_bf16 v[78:81], v[188:191], v[192:195], v[78:81]
	s_waitcnt lgkmcnt(0)
	v_mfma_f32_16x16x32_bf16 v[36:39], v[196:199], v[192:195], v[36:39]
	s_nop 7
	s_nop 1
	v_cvt_pk_bf16_f32 v78, v78, v79
	v_cvt_pk_bf16_f32 v79, v80, v81
	ds_write_b64 v97, v[78:79]
	s_cmp_lg_u32 s12, 1
	s_cbranch_scc1 .La1_UU_a_nz
	ds_write_b64 v97, v[174:175] offset:27648
	ds_write_b64 v97, v[174:175] offset:36864
	ds_write_b64 v97, v[174:175] offset:46080
	ds_write_b64 v97, v[174:175] offset:18432
.La1_UU_a_nz:
	v_cvt_pk_bf16_f32 v36, v36, v37
	v_cvt_pk_bf16_f32 v37, v38, v39
	ds_write_b64 v98, v[36:37]
	s_cmp_lg_u32 s12, 1
	s_cbranch_scc1 .La1_UU_b_nz
	ds_write_b64 v98, v[174:175] offset:27648
	ds_write_b64 v98, v[174:175] offset:36864
	ds_write_b64 v98, v[174:175] offset:46080
	ds_write_b64 v98, v[174:175] offset:18432

; __device__ __forceinline__ void st4_lds(LAS unsigned char* p, f32x4 v) { v2u w; w.x = pk2(v[0], v[1]); w.y = pk2(v[2], v[3]); *(LAS v2u*)p = w; }
; __device__ __forceinline__ f32x4 ld4_lds(const LAS unsigned char* p) { const v2u w = *(const LAS v2u*)p; return (f32x4){bflo(w.x), bfhi(w.x), bflo(w.y), bfhi(w.y)}; }
; #define LBAR() asm volatile("s_waitcnt lgkmcnt(0)\n\ts_barrier" ::: "memory")
; __device__ __forceinline__ void rwkv_chunk_group(Frame& F, int bc, unsigned long long& tsub) {
;     ...
;     for (int it = 0; it < 6; ++it) {
;         const int rM = (it & 1) ? L_AT : L_M, rMT = (it & 1) ? L_BT : L_MT, rTT = (it & 1) ? L_KT : L_TT;
;         const int wM = (it & 1) ? L_M : L_AT, wMT = (it & 1) ? L_MT : L_BT, wTT = (it & 1) ? L_TT : L_KT;
; #pragma unroll
;         for (int q = 0; q < 2; ++q) { const int tw = 2 * w + q, p0 = 16 * (tw >> 2), q0 = 16 * (tw & 3); const int o = (p0 + fr) * LD + (q0 + 4 * fq) * 2;
;             f32x4 tn = Z4, mn = Z4;
;             if (q0 <= p0) { tn = mm_tile(L + rM, LD, q0, L + rTT, LD, p0, 2, ld4_lds(L + rTT + o), fr, fq);
;                           }
;             if (q0 >= p0 && it < 5) mn = mm_tile(L + rMT, LD, q0, L + rM, LD, p0, 2, Z4, fr, fq);
;             st4_lds(L + wTT + o, tn); if (it < 5) { st4_lds(L + wM + o, mn); st4t_lds(L + wMT, p0 + fr, q0 + 4 * fq, mn); } }
;         LBAR();
.La1_done:
	v_mov_b32_e32 v78, v127
	v_mov_b32_e32 v79, v129
	v_add_u32_e32 v173, v106, v110
	v_add_u32_e32 v174, v106, v128
	v_add_u32_e32 v97, 0x12000, v127
	v_add_u32_e32 v98, 0x12000, v129
	v_mov_b32_e32 v102, 0
	v_mov_b32_e32 v103, 0
	v_add_u32_e32 v175, 0x12000, v173
	v_add_u32_e32 v96, 0x12000, v174
	s_and_b64 vcc, exec, s[78:79]
	s_cbranch_vccz .La2_FTFT
	s_and_b64 vcc, exec, s[84:85]
	s_cbranch_vccz .La2_TFTx
	ds_read_b64 v[242:243], v97 offset:18432
	ds_read_b128 v[176:179], v175 offset:0
	ds_read_b128 v[224:227], v132 offset:18432
	ds_read_b64_tr_b16 v[184:185], v253 offset:0
	ds_read_b64_tr_b16 v[186:187], v253 offset:576
	ds_read_b128 v[232:235], v132 offset:0
	ds_read_b64_tr_b16 v[192:193], v253 offset:32
	ds_read_b64_tr_b16 v[194:195], v253 offset:608
	ds_read_b128 v[180:183], v175 offset:64
	ds_read_b128 v[228:231], v132 offset:18496
	ds_read_b64_tr_b16 v[188:189], v253 offset:4608
	ds_read_b64_tr_b16 v[190:191], v253 offset:5184
	ds_read_b128 v[236:239], v132 offset:64
	ds_read_b64_tr_b16 v[196:197], v253 offset:4640
	ds_read_b64_tr_b16 v[198:199], v253 offset:5216
	s_waitcnt lgkmcnt(14)
	v_lshlrev_b32_e32 v240, 16, v242
	v_and_b32_e32 v241, 0xffff0000, v242
	v_lshlrev_b32_e32 v242, 16, v243
	v_and_b32_e32 v243, 0xffff0000, v243
	s_nop 1
	s_waitcnt lgkmcnt(12)
	v_mfma_f32_16x16x32_bf16 v[240:243], v[176:179], v[224:227], v[240:243]
	s_waitcnt lgkmcnt(9)
	v_mfma_f32_16x16x32_bf16 v[244:247], v[184:187], v[232:235], 0
	s_waitcnt lgkmcnt(7)
	v_mfma_f32_16x16x32_bf16 v[248:251], v[192:195], v[232:235], 0
	s_waitcnt lgkmcnt(5)
	v_mfma_f32_16x16x32_bf16 v[240:243], v[180:183], v[228:231], v[240:243]
	s_waitcnt lgkmcnt(2)
	v_mfma_f32_16x16x32_bf16 v[244:247], v[188:191], v[236:239], v[244:247]
	s_waitcnt lgkmcnt(0)
	v_mfma_f32_16x16x32_bf16 v[248:251], v[196:199], v[236:239], v[248:251]
	s_nop 7
	v_cvt_pk_bf16_f32 v176, v240, v241
	v_cvt_pk_bf16_f32 v177, v242, v243
	v_cvt_pk_bf16_f32 v184, v244, v245
	v_cvt_pk_bf16_f32 v185, v246, v247
	v_cvt_pk_bf16_f32 v192, v248, v249
	v_cvt_pk_bf16_f32 v193, v250, v251
	ds_write_b64 v127, v[176:177] offset:18432
	ds_write_b64 v127, v[184:185] offset:0
	ds_write_b64 v129, v[102:103] offset:18432
	ds_write_b64 v129, v[192:193] offset:0
	s_waitcnt lgkmcnt(0)
	s_barrier
	ds_read_b64 v[242:243], v127 offset:18432
	ds_read_b128 v[176:179], v173 offset:0
	ds_read_b128 v[224:227], v107 offset:18432
	ds_read_b64_tr_b16 v[184:185], v252 offset:0
	ds_read_b64_tr_b16 v[186:187], v252 offset:576
	ds_read_b128 v[232:235], v107 offset:0
	ds_read_b64_tr_b16 v[192:193], v252 offset:32
	ds_read_b64_tr_b16 v[194:195], v252 offset:608
	ds_read_b128 v[180:183], v173 offset:64
	ds_read_b128 v[228:231], v107 offset:18496
	ds_read_b64_tr_b16 v[188:189], v252 offset:4608
	ds_read_b64_tr_b16 v[190:191], v252 offset:5184
	ds_read_b128 v[236:239], v107 offset:64
	ds_read_b64_tr_b16 v[196:197], v252 offset:4640
	ds_read_b64_tr_b16 v[198:199], v252 offset:5216
	s_waitcnt lgkmcnt(14)
	v_lshlrev_b32_e32 v240, 16, v242
	v_and_b32_e32 v241, 0xffff0000, v242
	v_lshlrev_b32_e32 v242, 16, v243
	v_and_b32_e32 v243, 0xffff0000, v243
	s_nop 1
	s_waitcnt lgkmcnt(12)
	v_mfma_f32_16x16x32_bf16 v[240:243], v[176:179], v[224:227], v[240:243]
	s_waitcnt lgkmcnt(9)
	v_mfma_f32_16x16x32_bf16 v[244:247], v[184:187], v[232:235], 0
	s_waitcnt lgkmcnt(7)
	v_mfma_f32_16x16x32_bf16 v[248:251], v[192:195], v[232:235], 0
	s_waitcnt lgkmcnt(5)
	v_mfma_f32_16x16x32_bf16 v[240:243], v[180:183], v[228:231], v[240:243]
	s_waitcnt lgkmcnt(2)
	v_mfma_f32_16x16x32_bf16 v[244:247], v[188:191], v[236:239], v[244:247]
	s_waitcnt lgkmcnt(0)
	v_mfma_f32_16x16x32_bf16 v[248:251], v[196:199], v[236:239], v[248:251]
	s_nop 7
	v_cvt_pk_bf16_f32 v176, v240, v241
	v_cvt_pk_bf16_f32 v177, v242, v243
	v_cvt_pk_bf16_f32 v184, v244, v245
	v_cvt_pk_bf16_f32 v185, v246, v247
	v_cvt_pk_bf16_f32 v192, v248, v249
	v_cvt_pk_bf16_f32 v193, v250, v251
	ds_write_b64 v97, v[176:177] offset:18432
	ds_write_b64 v97, v[184:185] offset:0
	ds_write_b64 v98, v[192:193] offset:0
	s_waitcnt lgkmcnt(0)
	s_barrier
	ds_read_b64 v[242:243], v97 offset:18432
	ds_read_b128 v[176:179], v175 offset:0
	ds_read_b128 v[224:227], v132 offset:18432
	ds_read_b64_tr_b16 v[184:185], v253 offset:0
	ds_read_b64_tr_b16 v[186:187], v253 offset:576
	ds_read_b128 v[232:235], v132 offset:0
	ds_read_b64_tr_b16 v[192:193], v253 offset:32
	ds_read_b64_tr_b16 v[194:195], v253 offset:608
	ds_read_b128 v[180:183], v175 offset:64
	ds_read_b128 v[228:231], v132 offset:18496
	ds_read_b64_tr_b16 v[188:189], v253 offset:4608
	ds_read_b64_tr_b16 v[190:191], v253 offset:5184
	ds_read_b128 v[236:239], v132 offset:64
	ds_read_b64_tr_b16 v[196:197], v253 offset:4640
	ds_read_b64_tr_b16 v[198:199], v253 offset:5216
	s_waitcnt lgkmcnt(14)
	v_lshlrev_b32_e32 v240, 16, v242
	v_and_b32_e32 v241, 0xffff0000, v242
	v_lshlrev_b32_e32 v242, 16, v243
	v_and_b32_e32 v243, 0xffff0000, v243
	s_nop 1
	s_waitcnt lgkmcnt(12)
	v_mfma_f32_16x16x32_bf16 v[240:243], v[176:179], v[224:227], v[240:243]
	s_waitcnt lgkmcnt(9)
	v_mfma_f32_16x16x32_bf16 v[244:247], v[184:187], v[232:235], 0
	s_waitcnt lgkmcnt(7)
	v_mfma_f32_16x16x32_bf16 v[248:251], v[192:195], v[232:235], 0
	s_waitcnt lgkmcnt(5)
	v_mfma_f32_16x16x32_bf16 v[240:243], v[180:183], v[228:231], v[240:243]
	s_waitcnt lgkmcnt(2)
	v_mfma_f32_16x16x32_bf16 v[244:247], v[188:191], v[236:239], v[244:247]
	s_waitcnt lgkmcnt(0)
	v_mfma_f32_16x16x32_bf16 v[248:251], v[196:199], v[236:239], v[248:251]
	s_nop 7
	v_cvt_pk_bf16_f32 v176, v240, v241
	v_cvt_pk_bf16_f32 v177, v242, v243
	v_cvt_pk_bf16_f32 v184, v244, v245
	v_cvt_pk_bf16_f32 v185, v246, v247
	v_cvt_pk_bf16_f32 v192, v248, v249
	v_cvt_pk_bf16_f32 v193, v250, v251
	ds_write_b64 v127, v[176:177] offset:18432
	ds_write_b64 v127, v[184:185] offset:0
	ds_write_b64 v129, v[192:193] offset:0
	s_waitcnt lgkmcnt(0)
	s_barrier
; __device__ __forceinline__ void st4_lds(LAS unsigned char* p, f32x4 v) { v2u w; w.x = pk2(v[0], v[1]); w.y = pk2(v[2], v[3]); *(LAS v2u*)p = w; }
; __device__ __forceinline__ f32x4 ld4_lds(const LAS unsigned char* p) { const v2u w = *(const LAS v2u*)p; return (f32x4){bflo(w.x), bfhi(w.x), bflo(w.y), bfhi(w.y)}; }
; #define LBAR() asm volatile("s_waitcnt lgkmcnt(0)\n\ts_barrier" ::: "memory")
; __device__ __forceinline__ void rwkv_chunk_group(Frame& F, int bc, unsigned long long& tsub) {
;     ...
;     for (int it = 0; it < 6; ++it) {
;         const int rM = (it & 1) ? L_AT : L_M, rMT = (it & 1) ? L_BT : L_MT, rTT = (it & 1) ? L_KT : L_TT;
;         const int wM = (it & 1) ? L_M : L_AT, wMT = (it & 1) ? L_MT : L_BT, wTT = (it & 1) ? L_TT : L_KT;
; #pragma unroll
;         for (int q = 0; q < 2; ++q) { const int tw = 2 * w + q, p0 = 16 * (tw >> 2), q0 = 16 * (tw & 3); const int o = (p0 + fr) * LD + (q0 + 4 * fq) * 2;
;             f32x4 tn = Z4, mn = Z4;
;             if (q0 <= p0) { tn = mm_tile(L + rM, LD, q0, L + rTT, LD, p0, 2, ld4_lds(L + rTT + o), fr, fq);
;                           }
;             if (q0 >= p0 && it < 5) mn = mm_tile(L + rMT, LD, q0, L + rM, LD, p0, 2, Z4, fr, fq);
;             st4_lds(L + wTT + o, tn); if (it < 5) { st4_lds(L + wM + o, mn); st4t_lds(L + wMT, p0 + fr, q0 + 4 * fq, mn); } }
;         LBAR();
;     }
	ds_read_b64 v[242:243], v127 offset:18432
	ds_read_b128 v[176:179], v173 offset:0
	ds_read_b128 v[224:227], v107 offset:18432
	ds_read_b64_tr_b16 v[184:185], v252 offset:0
	ds_read_b64_tr_b16 v[186:187], v252 offset:576
	ds_read_b128 v[232:235], v107 offset:0
	ds_read_b64_tr_b16 v[192:193], v252 offset:32
	ds_read_b64_tr_b16 v[194:195], v252 offset:608
	ds_read_b128 v[180:183], v173 offset:64
	ds_read_b128 v[228:231], v107 offset:18496
	ds_read_b64_tr_b16 v[188:189], v252 offset:4608
	ds_read_b64_tr_b16 v[190:191], v252 offset:5184
	ds_read_b128 v[236:239], v107 offset:64
	ds_read_b64_tr_b16 v[196:197], v252 offset:4640
	ds_read_b64_tr_b16 v[198:199], v252 offset:5216
	s_waitcnt lgkmcnt(14)
	v_lshlrev_b32_e32 v240, 16, v242
	v_and_b32_e32 v241, 0xffff0000, v242
	v_lshlrev_b32_e32 v242, 16, v243
	v_and_b32_e32 v243, 0xffff0000, v243
	s_nop 1
	s_waitcnt lgkmcnt(12)
	v_mfma_f32_16x16x32_bf16 v[240:243], v[176:179], v[224:227], v[240:243]
	s_waitcnt lgkmcnt(9)
	v_mfma_f32_16x16x32_bf16 v[244:247], v[184:187], v[232:235], 0
	s_waitcnt lgkmcnt(7)
	v_mfma_f32_16x16x32_bf16 v[248:251], v[192:195], v[232:235], 0
	s_waitcnt lgkmcnt(5)
	v_mfma_f32_16x16x32_bf16 v[240:243], v[180:183], v[228:231], v[240:243]
	s_waitcnt lgkmcnt(2)
	v_mfma_f32_16x16x32_bf16 v[244:247], v[188:191], v[236:239], v[244:247]
	s_waitcnt lgkmcnt(0)
	v_mfma_f32_16x16x32_bf16 v[248:251], v[196:199], v[236:239], v[248:251]
	s_nop 7
	v_cvt_pk_bf16_f32 v176, v240, v241
	v_cvt_pk_bf16_f32 v177, v242, v243
	v_cvt_pk_bf16_f32 v184, v244, v245
	v_cvt_pk_bf16_f32 v185, v246, v247
	v_cvt_pk_bf16_f32 v192, v248, v249
	v_cvt_pk_bf16_f32 v193, v250, v251
	ds_write_b64 v97, v[176:177] offset:18432
	ds_write_b64 v97, v[184:185] offset:0
	ds_write_b64 v98, v[192:193] offset:0
	s_waitcnt lgkmcnt(0)
	s_barrier
	ds_read_b64 v[242:243], v97 offset:18432
	ds_read_b128 v[176:179], v175 offset:0
	ds_read_b128 v[224:227], v132 offset:18432
	ds_read_b64_tr_b16 v[184:185], v253 offset:0
	ds_read_b64_tr_b16 v[186:187], v253 offset:576
	ds_read_b128 v[232:235], v132 offset:0
	ds_read_b64_tr_b16 v[192:193], v253 offset:32
	ds_read_b64_tr_b16 v[194:195], v253 offset:608
	ds_read_b128 v[180:183], v175 offset:64
	ds_read_b128 v[228:231], v132 offset:18496
	ds_read_b64_tr_b16 v[188:189], v253 offset:4608
	ds_read_b64_tr_b16 v[190:191], v253 offset:5184
	ds_read_b128 v[236:239], v132 offset:64
	ds_read_b64_tr_b16 v[196:197], v253 offset:4640
	ds_read_b64_tr_b16 v[198:199], v253 offset:5216
	s_waitcnt lgkmcnt(14)
	v_lshlrev_b32_e32 v240, 16, v242
	v_and_b32_e32 v241, 0xffff0000, v242
	v_lshlrev_b32_e32 v242, 16, v243
	v_and_b32_e32 v243, 0xffff0000, v243
	s_nop 1
	s_waitcnt lgkmcnt(12)
	v_mfma_f32_16x16x32_bf16 v[240:243], v[176:179], v[224:227], v[240:243]
	s_waitcnt lgkmcnt(9)
	v_mfma_f32_16x16x32_bf16 v[244:247], v[184:187], v[232:235], 0
	s_waitcnt lgkmcnt(7)
	v_mfma_f32_16x16x32_bf16 v[248:251], v[192:195], v[232:235], 0
	s_waitcnt lgkmcnt(5)
	v_mfma_f32_16x16x32_bf16 v[240:243], v[180:183], v[228:231], v[240:243]
	s_waitcnt lgkmcnt(2)
	v_mfma_f32_16x16x32_bf16 v[244:247], v[188:191], v[236:239], v[244:247]
	s_waitcnt lgkmcnt(0)
	v_mfma_f32_16x16x32_bf16 v[248:251], v[196:199], v[236:239], v[248:251]
	s_nop 7
	v_cvt_pk_bf16_f32 v176, v240, v241
	v_cvt_pk_bf16_f32 v177, v242, v243
	v_cvt_pk_bf16_f32 v184, v244, v245
	v_cvt_pk_bf16_f32 v185, v246, v247
	v_cvt_pk_bf16_f32 v192, v248, v249
	v_cvt_pk_bf16_f32 v193, v250, v251
	ds_write_b64 v127, v[176:177] offset:18432
	ds_write_b64 v127, v[184:185] offset:0
	ds_write_b64 v129, v[192:193] offset:0
	s_waitcnt lgkmcnt(0)
	s_barrier
	ds_read_b64 v[242:243], v127 offset:18432
	ds_read_b128 v[176:179], v173 offset:0
	ds_read_b128 v[224:227], v107 offset:18432
	ds_read_b128 v[180:183], v173 offset:64
	ds_read_b128 v[228:231], v107 offset:18496
	s_waitcnt lgkmcnt(4)
	v_lshlrev_b32_e32 v240, 16, v242
	v_and_b32_e32 v241, 0xffff0000, v242
	v_lshlrev_b32_e32 v242, 16, v243
	v_and_b32_e32 v243, 0xffff0000, v243
	s_nop 1
	s_waitcnt lgkmcnt(2)
	v_mfma_f32_16x16x32_bf16 v[240:243], v[176:179], v[224:227], v[240:243]
	s_waitcnt lgkmcnt(0)
	v_mfma_f32_16x16x32_bf16 v[240:243], v[180:183], v[228:231], v[240:243]
	s_nop 7
	v_cvt_pk_bf16_f32 v176, v240, v241
	v_cvt_pk_bf16_f32 v177, v242, v243
	ds_write_b64 v97, v[176:177] offset:18432
	s_waitcnt lgkmcnt(0)
	s_barrier
	s_branch .La2_done
